# grid barrier: non-leader workgroups poll the cross-XCD generation word directly (one hop less), leader's local release add removed
# speedup vs baseline: 1.0048x; 1.0048x over previous
.LBB0_735:
	s_or_b64 exec, exec, s[4:5]
	v_cvt_f32_u32_e32 v5, v3
	s_waitcnt vmcnt(0)
	v_readfirstlane_b32 s2, v4
	v_sub_u32_e32 v4, 0, v3
	v_rcp_iflag_f32_e32 v5, v5
	v_add_u32_e32 v6, s2, v0
	v_mul_f32_e32 v5, 0x4f7ffffe, v5
	v_cvt_u32_f32_e32 v5, v5
	v_mul_lo_u32 v0, v4, v5
	v_mul_hi_u32 v0, v5, v0
	v_add_u32_e32 v0, v5, v0
	v_mul_hi_u32 v0, v6, v0
	v_mul_lo_u32 v4, v0, v3
	v_sub_u32_e32 v4, v6, v4
	v_add_u32_e32 v5, 1, v0
	v_cmp_ge_u32_e32 vcc, v4, v3
	s_nop 1
	v_cndmask_b32_e32 v0, v0, v5, vcc
	v_sub_u32_e32 v5, v4, v3
	v_cndmask_b32_e32 v4, v4, v5, vcc
	v_add_u32_e32 v5, 1, v0
	v_cmp_ge_u32_e32 vcc, v4, v3
	v_add_u32_e32 v4, 1, v6
	s_nop 0
	v_cndmask_b32_e32 v0, v0, v5, vcc
	v_mul_lo_u32 v5, v3, v0
	v_add_u32_e32 v3, v5, v3
	v_cmp_ne_u32_e32 vcc, v4, v3
	s_and_saveexec_b64 s[4:5], vcc
	s_xor_b64 s[4:5], exec, s[4:5]
	s_cbranch_execz .LBB0_749
	v_readlane_b32 s6, v237, 47
	v_readlane_b32 s7, v237, 48
	s_waitcnt lgkmcnt(0)
	s_nop 3
	global_load_dword v2, v1, s[6:7] sc1
	s_waitcnt vmcnt(0)
	v_cmp_eq_u32_e32 vcc, v2, v0
	s_and_saveexec_b64 s[6:7], vcc
	s_cbranch_execz .LBB0_748
	s_mov_b32 s2, 1
	s_mov_b64 s[8:9], 0
	s_branch .LBB0_739

.LBB0_766:
	s_or_b64 exec, exec, s[4:5]
	s_mov_b64 s[4:5], exec
	v_mbcnt_lo_u32_b32 v0, s4, 0
	v_mbcnt_hi_u32_b32 v0, s5, v0
	v_cmp_eq_u32_e32 vcc, 0, v0
	s_waitcnt vmcnt(0)
	buffer_inv sc1
	s_and_saveexec_b64 s[6:7], vcc
	s_cbranch_execz .LBB0_19
	s_branch .LBB0_19
